# v63 + SADDR-form LDS-DMA in the P6 K-loop (16 v_lshl_add_u64 removed per iteration)
# speedup vs baseline: 1.0079x; 1.0079x over previous
.LBB0_1058:
	ds_read_b128 v[128:131], v194
	ds_read_b128 v[132:135], v194 offset:1024
	ds_read_b128 v[136:139], v194 offset:2048
	ds_read_b128 v[140:143], v194 offset:3072
	ds_read_b128 v[144:147], v195
	ds_read_b128 v[148:151], v195 offset:1024
	ds_read_b128 v[152:155], v195 offset:2048
	ds_read_b128 v[156:159], v195 offset:3072
	s_add_u32 s2, s0, 0x100
	s_addc_u32 s3, s1, 0
	s_cmpk_eq_i32 s39, 0xa8
	s_cselect_b32 s37, s31, s3
	s_cselect_b32 s36, s30, s2
	s_cselect_b32 s5, s7, s38
	s_cselect_b32 s4, s6, s29
	s_add_i32 m0, s27, 0xc000
	ds_read_b128 v[172:175], v196
	ds_read_b128 v[176:179], v196 offset:1024
	ds_read_b128 v[180:183], v196 offset:2048
	ds_read_b128 v[184:187], v196 offset:3072
	ds_read_b128 v[200:203], v196 offset:4096
	ds_read_b128 v[204:207], v196 offset:5120
	ds_read_b128 v[208:211], v196 offset:6144
	ds_read_b128 v[212:215], v196 offset:7168
	global_load_lds_dwordx4 v168, s[0:1]
	s_add_i32 m0, s27, 0xe000
	s_nop 0
	global_load_lds_dwordx4 v170, s[0:1]
	s_waitcnt vmcnt(8)
	s_waitcnt lgkmcnt(0)
	s_barrier
	s_waitcnt lgkmcnt(0)
	v_mfma_f32_16x16x32_bf16 v[12:15], v[128:131], v[172:175], v[12:15]
	v_mfma_f32_16x16x32_bf16 v[8:11], v[136:139], v[172:175], v[8:11]
	v_mfma_f32_16x16x32_bf16 v[36:39], v[128:131], v[180:183], v[36:39]
	v_mfma_f32_16x16x32_bf16 v[32:35], v[136:139], v[180:183], v[32:35]
	v_mfma_f32_16x16x32_bf16 v[44:47], v[128:131], v[200:203], v[44:47]
	v_mfma_f32_16x16x32_bf16 v[40:43], v[136:139], v[200:203], v[40:43]
	v_mfma_f32_16x16x32_bf16 v[64:67], v[128:131], v[208:211], v[64:67]
	v_mfma_f32_16x16x32_bf16 v[56:59], v[136:139], v[208:211], v[56:59]
	v_mfma_f32_16x16x32_bf16 v[12:15], v[132:135], v[176:179], v[12:15]
	v_mfma_f32_16x16x32_bf16 v[8:11], v[140:143], v[176:179], v[8:11]
	v_mfma_f32_16x16x32_bf16 v[36:39], v[132:135], v[184:187], v[36:39]
	v_mfma_f32_16x16x32_bf16 v[32:35], v[140:143], v[184:187], v[32:35]
	v_mfma_f32_16x16x32_bf16 v[44:47], v[132:135], v[204:207], v[44:47]
	v_mfma_f32_16x16x32_bf16 v[40:43], v[140:143], v[204:207], v[40:43]
	v_mfma_f32_16x16x32_bf16 v[64:67], v[132:135], v[212:215], v[64:67]
	v_mfma_f32_16x16x32_bf16 v[56:59], v[140:143], v[212:215], v[56:59]
	v_mfma_f32_16x16x32_bf16 v[4:7], v[144:147], v[172:175], v[4:7]
	v_mfma_f32_16x16x32_bf16 v[0:3], v[152:155], v[172:175], v[0:3]
	v_mfma_f32_16x16x32_bf16 v[24:27], v[144:147], v[180:183], v[24:27]
	v_mfma_f32_16x16x32_bf16 v[16:19], v[152:155], v[180:183], v[16:19]
	v_mfma_f32_16x16x32_bf16 v[28:31], v[144:147], v[200:203], v[28:31]
	v_mfma_f32_16x16x32_bf16 v[20:23], v[152:155], v[200:203], v[20:23]
	v_mfma_f32_16x16x32_bf16 v[52:55], v[144:147], v[208:211], v[52:55]
	v_mfma_f32_16x16x32_bf16 v[48:51], v[152:155], v[208:211], v[48:51]
	v_mfma_f32_16x16x32_bf16 v[4:7], v[148:151], v[176:179], v[4:7]
	v_mfma_f32_16x16x32_bf16 v[0:3], v[156:159], v[176:179], v[0:3]
	v_mfma_f32_16x16x32_bf16 v[24:27], v[148:151], v[184:187], v[24:27]
	v_mfma_f32_16x16x32_bf16 v[16:19], v[156:159], v[184:187], v[16:19]
	v_mfma_f32_16x16x32_bf16 v[28:31], v[148:151], v[204:207], v[28:31]
	v_mfma_f32_16x16x32_bf16 v[20:23], v[156:159], v[204:207], v[20:23]
	v_mfma_f32_16x16x32_bf16 v[52:55], v[148:151], v[212:215], v[52:55]
	v_mfma_f32_16x16x32_bf16 v[48:51], v[156:159], v[212:215], v[48:51]
	s_barrier
	s_add_i32 s0, s17, s25
	s_mov_b32 m0, s0
	ds_read_b128 v[172:175], v196 offset:16384
	ds_read_b128 v[176:179], v196 offset:17408
	ds_read_b128 v[180:183], v196 offset:18432
	ds_read_b128 v[184:187], v196 offset:19456
	ds_read_b128 v[200:203], v196 offset:20480
	ds_read_b128 v[204:207], v196 offset:21504
	ds_read_b128 v[208:211], v196 offset:22528
	ds_read_b128 v[212:215], v196 offset:23552
	global_load_lds_dwordx4 v162, s[4:5]
	s_add_i32 m0, s0, 0x2000
	s_add_u32 s0, s4, 0x2b0000
	s_addc_u32 s1, s5, 0
	s_add_i32 s40, s55, s25
	global_load_lds_dwordx4 v166, s[4:5]
	s_mov_b32 m0, s40
	s_nop 0
	global_load_lds_dwordx4 v162, s[0:1]
	s_add_i32 m0, s40, 0x2000
	s_nop 0
	global_load_lds_dwordx4 v166, s[0:1]
	s_mov_b32 m0, s27
	s_nop 0
	global_load_lds_dwordx4 v160, s[36:37]
	s_mov_b32 m0, s33
	s_nop 0
	global_load_lds_dwordx4 v164, s[36:37]
	s_waitcnt vmcnt(8)
	s_waitcnt lgkmcnt(0)
	s_barrier
	s_waitcnt lgkmcnt(0)
	v_mfma_f32_16x16x32_bf16 v[76:79], v[128:131], v[172:175], v[76:79]
	v_mfma_f32_16x16x32_bf16 v[72:75], v[136:139], v[172:175], v[72:75]
	v_mfma_f32_16x16x32_bf16 v[92:95], v[128:131], v[180:183], v[92:95]
	v_mfma_f32_16x16x32_bf16 v[88:91], v[136:139], v[180:183], v[88:91]
	v_mfma_f32_16x16x32_bf16 v[108:111], v[128:131], v[200:203], v[108:111]
	v_mfma_f32_16x16x32_bf16 v[104:107], v[136:139], v[200:203], v[104:107]
	v_mfma_f32_16x16x32_bf16 v[124:127], v[128:131], v[208:211], v[124:127]
	v_mfma_f32_16x16x32_bf16 v[120:123], v[136:139], v[208:211], v[120:123]
	v_mfma_f32_16x16x32_bf16 v[76:79], v[132:135], v[176:179], v[76:79]
	v_mfma_f32_16x16x32_bf16 v[72:75], v[140:143], v[176:179], v[72:75]
	v_mfma_f32_16x16x32_bf16 v[92:95], v[132:135], v[184:187], v[92:95]
	v_mfma_f32_16x16x32_bf16 v[88:91], v[140:143], v[184:187], v[88:91]
	v_mfma_f32_16x16x32_bf16 v[108:111], v[132:135], v[204:207], v[108:111]
	v_mfma_f32_16x16x32_bf16 v[104:107], v[140:143], v[204:207], v[104:107]
	v_mfma_f32_16x16x32_bf16 v[124:127], v[132:135], v[212:215], v[124:127]
	v_mfma_f32_16x16x32_bf16 v[120:123], v[140:143], v[212:215], v[120:123]
	v_mfma_f32_16x16x32_bf16 v[68:71], v[144:147], v[172:175], v[68:71]
	v_mfma_f32_16x16x32_bf16 v[60:63], v[152:155], v[172:175], v[60:63]
	v_mfma_f32_16x16x32_bf16 v[84:87], v[144:147], v[180:183], v[84:87]
	v_mfma_f32_16x16x32_bf16 v[80:83], v[152:155], v[180:183], v[80:83]
	v_mfma_f32_16x16x32_bf16 v[100:103], v[144:147], v[200:203], v[100:103]
	v_mfma_f32_16x16x32_bf16 v[96:99], v[152:155], v[200:203], v[96:99]
	v_mfma_f32_16x16x32_bf16 v[116:119], v[144:147], v[208:211], v[116:119]
	v_mfma_f32_16x16x32_bf16 v[112:115], v[152:155], v[208:211], v[112:115]
	v_mfma_f32_16x16x32_bf16 v[68:71], v[148:151], v[176:179], v[68:71]
	v_mfma_f32_16x16x32_bf16 v[60:63], v[156:159], v[176:179], v[60:63]
	v_mfma_f32_16x16x32_bf16 v[84:87], v[148:151], v[184:187], v[84:87]
	v_mfma_f32_16x16x32_bf16 v[80:83], v[156:159], v[184:187], v[80:83]
	v_mfma_f32_16x16x32_bf16 v[100:103], v[148:151], v[204:207], v[100:103]
	v_mfma_f32_16x16x32_bf16 v[96:99], v[156:159], v[204:207], v[96:99]
	v_mfma_f32_16x16x32_bf16 v[116:119], v[148:151], v[212:215], v[116:119]
	v_mfma_f32_16x16x32_bf16 v[112:115], v[156:159], v[212:215], v[112:115]
	s_barrier
	v_add_u32_e32 v140, s56, v193
	v_add_u32_e32 v156, s57, v193
	ds_read_b128 v[128:131], v140
	ds_read_b128 v[132:135], v140 offset:1024
	ds_read_b128 v[136:139], v140 offset:2048
	ds_read_b128 v[140:143], v140 offset:3072
	ds_read_b128 v[144:147], v156
	ds_read_b128 v[148:151], v156 offset:1024
	ds_read_b128 v[152:155], v156 offset:2048
	ds_read_b128 v[156:159], v156 offset:3072
	s_add_u32 s0, s36, 0x2b0000
	s_addc_u32 s1, s37, 0
	s_mov_b32 m0, s46
	ds_read_b128 v[172:175], v196 offset:32768
	ds_read_b128 v[176:179], v196 offset:33792
	ds_read_b128 v[180:183], v196 offset:34816
	ds_read_b128 v[184:187], v196 offset:35840
	ds_read_b128 v[200:203], v196 offset:36864
	ds_read_b128 v[204:207], v196 offset:37888
	ds_read_b128 v[208:211], v196 offset:38912
	ds_read_b128 v[212:215], v196 offset:39936
	global_load_lds_dwordx4 v160, s[0:1]
	s_mov_b32 m0, s47
	s_nop 0
	global_load_lds_dwordx4 v164, s[0:1]
	s_waitcnt vmcnt(8)
	s_waitcnt lgkmcnt(0)
	s_barrier
	s_waitcnt lgkmcnt(0)
	v_mfma_f32_16x16x32_bf16 v[12:15], v[128:131], v[172:175], v[12:15]
	v_mfma_f32_16x16x32_bf16 v[8:11], v[136:139], v[172:175], v[8:11]
	v_mfma_f32_16x16x32_bf16 v[36:39], v[128:131], v[180:183], v[36:39]
	v_mfma_f32_16x16x32_bf16 v[32:35], v[136:139], v[180:183], v[32:35]
	v_mfma_f32_16x16x32_bf16 v[44:47], v[128:131], v[200:203], v[44:47]
	v_mfma_f32_16x16x32_bf16 v[40:43], v[136:139], v[200:203], v[40:43]
	v_mfma_f32_16x16x32_bf16 v[64:67], v[128:131], v[208:211], v[64:67]
	v_mfma_f32_16x16x32_bf16 v[56:59], v[136:139], v[208:211], v[56:59]
	v_mfma_f32_16x16x32_bf16 v[12:15], v[132:135], v[176:179], v[12:15]
	v_mfma_f32_16x16x32_bf16 v[8:11], v[140:143], v[176:179], v[8:11]
	v_mfma_f32_16x16x32_bf16 v[36:39], v[132:135], v[184:187], v[36:39]
	v_mfma_f32_16x16x32_bf16 v[32:35], v[140:143], v[184:187], v[32:35]
	v_mfma_f32_16x16x32_bf16 v[44:47], v[132:135], v[204:207], v[44:47]
	v_mfma_f32_16x16x32_bf16 v[40:43], v[140:143], v[204:207], v[40:43]
	v_mfma_f32_16x16x32_bf16 v[64:67], v[132:135], v[212:215], v[64:67]
	v_mfma_f32_16x16x32_bf16 v[56:59], v[140:143], v[212:215], v[56:59]
	v_mfma_f32_16x16x32_bf16 v[4:7], v[144:147], v[172:175], v[4:7]
	v_mfma_f32_16x16x32_bf16 v[0:3], v[152:155], v[172:175], v[0:3]
	v_mfma_f32_16x16x32_bf16 v[24:27], v[144:147], v[180:183], v[24:27]
	v_mfma_f32_16x16x32_bf16 v[16:19], v[152:155], v[180:183], v[16:19]
	v_mfma_f32_16x16x32_bf16 v[28:31], v[144:147], v[200:203], v[28:31]
	v_mfma_f32_16x16x32_bf16 v[20:23], v[152:155], v[200:203], v[20:23]
	v_mfma_f32_16x16x32_bf16 v[52:55], v[144:147], v[208:211], v[52:55]
	v_mfma_f32_16x16x32_bf16 v[48:51], v[152:155], v[208:211], v[48:51]
	v_mfma_f32_16x16x32_bf16 v[4:7], v[148:151], v[176:179], v[4:7]
	v_mfma_f32_16x16x32_bf16 v[0:3], v[156:159], v[176:179], v[0:3]
	v_mfma_f32_16x16x32_bf16 v[24:27], v[148:151], v[184:187], v[24:27]
	v_mfma_f32_16x16x32_bf16 v[16:19], v[156:159], v[184:187], v[16:19]
	v_mfma_f32_16x16x32_bf16 v[28:31], v[148:151], v[204:207], v[28:31]
	v_mfma_f32_16x16x32_bf16 v[20:23], v[156:159], v[204:207], v[20:23]
	v_mfma_f32_16x16x32_bf16 v[52:55], v[148:151], v[212:215], v[52:55]
	v_mfma_f32_16x16x32_bf16 v[48:51], v[156:159], v[212:215], v[48:51]
	s_barrier
	s_add_i32 s0, s56, s25
	s_add_u32 s98, s4, 0x80
	s_addc_u32 s99, s5, 0
	s_add_u32 s100, s36, 0x80
	s_addc_u32 s101, s37, 0
	s_mov_b32 m0, s0
	ds_read_b128 v[172:175], v196 offset:49152
	ds_read_b128 v[176:179], v196 offset:50176
	ds_read_b128 v[180:183], v196 offset:51200
	ds_read_b128 v[184:187], v196 offset:52224
	ds_read_b128 v[200:203], v196 offset:53248
	ds_read_b128 v[204:207], v196 offset:54272
	ds_read_b128 v[208:211], v196 offset:55296
	ds_read_b128 v[212:215], v196 offset:56320
	global_load_lds_dwordx4 v162, s[98:99]
	s_add_i32 m0, s0, 0x2000
	s_add_u32 s0, s4, 0x2b0080
	s_addc_u32 s1, s5, 0
	s_add_i32 s4, s57, s25
	global_load_lds_dwordx4 v166, s[98:99]
	s_mov_b32 m0, s4
	s_nop 0
	global_load_lds_dwordx4 v162, s[0:1]
	s_add_i32 m0, s4, 0x2000
	s_nop 0
	global_load_lds_dwordx4 v166, s[0:1]
	s_mov_b32 m0, s52
	s_nop 0
	global_load_lds_dwordx4 v160, s[100:101]
	s_mov_b32 m0, s53
	s_nop 0
	global_load_lds_dwordx4 v164, s[100:101]
	s_waitcnt vmcnt(8)
	s_waitcnt lgkmcnt(0)
	s_barrier
	s_waitcnt lgkmcnt(0)
	v_mfma_f32_16x16x32_bf16 v[76:79], v[128:131], v[172:175], v[76:79]
	v_mfma_f32_16x16x32_bf16 v[72:75], v[136:139], v[172:175], v[72:75]
	v_mfma_f32_16x16x32_bf16 v[92:95], v[128:131], v[180:183], v[92:95]
	v_mfma_f32_16x16x32_bf16 v[88:91], v[136:139], v[180:183], v[88:91]
	v_mfma_f32_16x16x32_bf16 v[108:111], v[128:131], v[200:203], v[108:111]
	v_mfma_f32_16x16x32_bf16 v[104:107], v[136:139], v[200:203], v[104:107]
	v_mfma_f32_16x16x32_bf16 v[124:127], v[128:131], v[208:211], v[124:127]
	v_mfma_f32_16x16x32_bf16 v[120:123], v[136:139], v[208:211], v[120:123]
	v_mfma_f32_16x16x32_bf16 v[76:79], v[132:135], v[176:179], v[76:79]
	v_mfma_f32_16x16x32_bf16 v[72:75], v[140:143], v[176:179], v[72:75]
	v_mfma_f32_16x16x32_bf16 v[92:95], v[132:135], v[184:187], v[92:95]
	v_mfma_f32_16x16x32_bf16 v[88:91], v[140:143], v[184:187], v[88:91]
	v_mfma_f32_16x16x32_bf16 v[108:111], v[132:135], v[204:207], v[108:111]
	v_mfma_f32_16x16x32_bf16 v[104:107], v[140:143], v[204:207], v[104:107]
	v_mfma_f32_16x16x32_bf16 v[124:127], v[132:135], v[212:215], v[124:127]
	v_mfma_f32_16x16x32_bf16 v[120:123], v[140:143], v[212:215], v[120:123]
	v_mfma_f32_16x16x32_bf16 v[68:71], v[144:147], v[172:175], v[68:71]
	v_mfma_f32_16x16x32_bf16 v[60:63], v[152:155], v[172:175], v[60:63]
	v_mfma_f32_16x16x32_bf16 v[84:87], v[144:147], v[180:183], v[84:87]
	v_mfma_f32_16x16x32_bf16 v[80:83], v[152:155], v[180:183], v[80:83]
	v_mfma_f32_16x16x32_bf16 v[100:103], v[144:147], v[200:203], v[100:103]
	v_mfma_f32_16x16x32_bf16 v[96:99], v[152:155], v[200:203], v[96:99]
	v_mfma_f32_16x16x32_bf16 v[116:119], v[144:147], v[208:211], v[116:119]
	v_mfma_f32_16x16x32_bf16 v[112:115], v[152:155], v[208:211], v[112:115]
	v_mfma_f32_16x16x32_bf16 v[68:71], v[148:151], v[176:179], v[68:71]
	v_mfma_f32_16x16x32_bf16 v[60:63], v[156:159], v[176:179], v[60:63]
	v_mfma_f32_16x16x32_bf16 v[84:87], v[148:151], v[184:187], v[84:87]
	v_mfma_f32_16x16x32_bf16 v[80:83], v[156:159], v[184:187], v[80:83]
	v_mfma_f32_16x16x32_bf16 v[100:103], v[148:151], v[204:207], v[100:103]
	v_mfma_f32_16x16x32_bf16 v[96:99], v[156:159], v[204:207], v[96:99]
	v_mfma_f32_16x16x32_bf16 v[116:119], v[148:151], v[212:215], v[116:119]
	v_mfma_f32_16x16x32_bf16 v[112:115], v[156:159], v[212:215], v[112:115]
	s_barrier
	s_add_i32 s39, s39, 2
	s_add_u32 s29, s29, 0x100
	s_addc_u32 s38, s38, 0
	s_cmpk_gt_u32 s39, 0xa9
	s_mov_b64 s[0:1], s[2:3]
	s_cbranch_scc0 .LBB0_1058
	s_and_b64 vcc, exec, s[20:21]
	s_cbranch_vccz .LBB0_1061
	s_barrier
